# v62 minus GEMM-side pacing + P1b's last 512 units run by the GEMM half of P2 behind a scan-progress counter (row-tile permutation so they alias consumed xbc chunks)
# speedup vs baseline: 1.0219x; 1.0140x over previous
.LBB0_380:
	s_or_b64 exec, exec, s[94:95]
	s_add_i32 s14, s15, 1
	s_cmp_lt_u32 s14, s0
	s_cselect_b32 s15, s14, s15
	s_lshl_b32 s16, s15, 6
	s_add_i32 s16, s16, s97
	s_cmp_eq_u32 s15, 0
	s_cselect_b32 s15, 0, 0x1000
	s_waitcnt lgkmcnt(0)
	s_barrier
	s_waitcnt vmcnt(0)
	ds_write_b128 v230, v[136:139]
	ds_write_b128 v230, v[140:143] offset:128
	ds_write_b128 v230, v[144:147] offset:256
	ds_write_b128 v230, v[148:151] offset:384
	v_readlane_b32 s98, v255, 6
	s_cmpk_gt_u32 s98, 0x7f
	s_cbranch_scc1 .Lprog_skip
	v_readlane_b32 s100, v255, 1
	v_readlane_b32 s101, v255, 2
	s_lshr_b32 s98, s98, 3
	s_lshl_b32 s98, s98, 5
	s_add_u32 s100, s100, s98
	s_addc_u32 s101, s101, 0
	s_add_u32 s100, s100, 0x80000
	s_addc_u32 s101, s101, 0
	v_cmp_eq_u32_e64 s[98:99], 0, v179
	s_and_saveexec_b64 s[98:99], s[98:99]
	s_cbranch_execz .Lprog_rest
	v_mov_b32_e32 v2, 0
	v_mov_b32_e32 v3, 1
	global_atomic_add v2, v3, s[100:101]
.Lprog_rest:
	s_mov_b64 exec, s[98:99]
.Lprog_skip:
	v_readlane_b32 s98, v254, 52
	v_readlane_b32 s99, v254, 53
	v_readfirstlane_b32 s100, v1
	s_nop 3
	v_subrev_u32_e32 v151, s98, v176
	s_cmp_lg_u32 s100, 0
	s_cselect_b32 s101, 0x1000, s15
	s_add_i32 s100, s100, s16
	s_lshl_b32 s100, s100, 13
	s_add_u32 s98, s98, s100
	s_addc_u32 s99, s99, 0
	s_mul_i32 s100, s101, 6
	s_sub_u32 s98, s98, s100
	s_subb_u32 s99, s99, 0
	s_lshl_b32 s100, s101, 1
	v_add_u32_e32 v2, s16, v159
	v_ashrrev_i32_e32 v3, 31, v2
	v_lshlrev_b64 v[2:3], 7, v[2:3]
	v_lshl_add_u64 v[2:3], s[90:91], 0, v[2:3]
	global_load_dword v153, v[2:3], off
	ds_read_b128 v[84:87], v180
	ds_read_b128 v[88:91], v181 offset:17408
	ds_read_b128 v[92:95], v181 offset:21760
	global_load_dword v250, v151, s[98:99]
	ds_read_b128 v[68:71], v180 offset:64
	ds_read_b128 v[96:99], v181 offset:17472
	ds_read_b128 v[100:103], v181 offset:21824
	ds_read_b128 v[72:75], v180 offset:128
	ds_read_b128 v[76:79], v181 offset:17536
	v_add_u32_e32 v192, v178, v228
	ds_read_b128 v[80:83], v181 offset:21888
	ds_read_b128 v[104:107], v180 offset:192
	s_waitcnt lgkmcnt(8)
	v_mfma_f32_16x16x32_bf16 v[88:91], v[84:87], v[88:91], 0
	s_add_u32 s98, s98, s100
	s_addc_u32 s99, s99, 0
	global_load_dword v251, v151, s[98:99]
	ds_read_b128 v[108:111], v181 offset:17600
	s_waitcnt lgkmcnt(8)
	v_mfma_f32_16x16x32_bf16 v[84:87], v[84:87], v[92:95], 0
	ds_read_b128 v[112:115], v181 offset:21952
	s_waitcnt lgkmcnt(7)
	v_mfma_f32_16x16x32_bf16 v[88:91], v[68:71], v[96:99], v[88:91]
	s_waitcnt lgkmcnt(6)
	v_mfma_f32_16x16x32_bf16 v[84:87], v[68:71], v[100:103], v[84:87]
	s_waitcnt lgkmcnt(4)
	v_mfma_f32_16x16x32_bf16 v[88:91], v[72:75], v[76:79], v[88:91]
	s_add_u32 s98, s98, s100
	s_addc_u32 s99, s99, 0
	global_load_dword v252, v151, s[98:99]
	s_waitcnt lgkmcnt(3)
	v_mfma_f32_16x16x32_bf16 v[84:87], v[72:75], v[80:83], v[84:87]
	s_waitcnt lgkmcnt(1)
	v_mfma_f32_16x16x32_bf16 v[88:91], v[104:107], v[108:111], v[88:91]
	s_waitcnt lgkmcnt(0)
	v_mfma_f32_16x16x32_bf16 v[84:87], v[104:107], v[112:115], v[84:87]
	s_nop 7
	ds_write2_b32 v202, v88, v84 offset1:16
	ds_write2_b32 v202, v89, v85 offset0:68 offset1:84
	ds_write2_b32 v202, v90, v86 offset0:136 offset1:152
	s_add_u32 s98, s98, s100
	s_addc_u32 s99, s99, 0
	global_load_dword v249, v151, s[98:99]
	ds_write2_b32 v202, v91, v87 offset0:204 offset1:220
	ds_read2_b64 v[92:95], v224 offset1:4
	ds_read2_b64 v[100:103], v225 offset1:4
	ds_read2_b64 v[108:111], v226 offset1:4
	ds_read2_b64 v[116:119], v227 offset1:4
	ds_read2_b64 v[124:127], v224 offset0:8 offset1:12
	ds_read2_b64 v[68:71], v225 offset0:8 offset1:12
	ds_read2_b64 v[72:75], v226 offset0:8 offset1:12
	ds_read2_b64 v[76:79], v227 offset0:8 offset1:12
	v_cvt_pk_bf16_f32 v84, v4, v5
	s_add_u32 s98, s98, 0x2000
	s_addc_u32 s99, s99, 0
	global_load_dword v248, v151, s[98:99]
	v_cvt_pk_bf16_f32 v85, v6, v7
	v_cvt_pk_bf16_f32 v86, v12, v13
	v_cvt_pk_bf16_f32 v87, v14, v15
	v_cvt_pk_bf16_f32 v88, v8, v9
	v_cvt_pk_bf16_f32 v89, v10, v11
	v_cvt_pk_bf16_f32 v90, v16, v17
	v_cvt_pk_bf16_f32 v91, v18, v19
	ds_read2_b64 v[80:83], v224 offset0:16 offset1:20
	s_waitcnt lgkmcnt(8)
	v_mfma_f32_16x16x32_bf16 v[96:99], v[92:95], v[84:87], 0
	s_add_u32 s98, s98, 0x2000
	s_addc_u32 s99, s99, 0
	global_load_dword v247, v151, s[98:99]
	v_mfma_f32_16x16x32_bf16 v[92:95], v[92:95], v[88:91], 0
	ds_read2_b64 v[128:131], v225 offset0:16 offset1:20
	s_waitcnt lgkmcnt(8)
	v_mfma_f32_16x16x32_bf16 v[104:107], v[100:103], v[84:87], 0
	v_mfma_f32_16x16x32_bf16 v[100:103], v[100:103], v[88:91], 0
	ds_read2_b64 v[132:135], v226 offset0:16 offset1:20
	s_waitcnt lgkmcnt(8)
	v_mfma_f32_16x16x32_bf16 v[112:115], v[108:111], v[84:87], 0
	v_mfma_f32_16x16x32_bf16 v[108:111], v[108:111], v[88:91], 0
	ds_read2_b64 v[136:139], v227 offset0:16 offset1:20
	s_add_u32 s98, s98, 0x2000
	s_addc_u32 s99, s99, 0
	global_load_dword v246, v151, s[98:99]
	s_waitcnt lgkmcnt(8)
	v_mfma_f32_16x16x32_bf16 v[84:87], v[116:119], v[84:87], 0
	v_mfma_f32_16x16x32_bf16 v[88:91], v[116:119], v[88:91], 0
	v_cvt_pk_bf16_f32 v116, v20, v21
	v_cvt_pk_bf16_f32 v117, v22, v23
	v_cvt_pk_bf16_f32 v118, v28, v29
	v_cvt_pk_bf16_f32 v119, v30, v31
	v_cvt_pk_bf16_f32 v120, v24, v25
	v_cvt_pk_bf16_f32 v121, v26, v27
	v_cvt_pk_bf16_f32 v122, v32, v33
	s_add_u32 s98, s98, 0x2000
	s_addc_u32 s99, s99, 0
	global_load_dword v245, v151, s[98:99]
	v_cvt_pk_bf16_f32 v123, v34, v35
	ds_read2_b64 v[140:143], v224 offset0:24 offset1:28
	s_waitcnt lgkmcnt(8)
	v_mfma_f32_16x16x32_bf16 v[96:99], v[124:127], v[116:119], v[96:99]
	v_mfma_f32_16x16x32_bf16 v[92:95], v[124:127], v[120:123], v[92:95]
	ds_read2_b64 v[144:147], v225 offset0:24 offset1:28
	s_waitcnt lgkmcnt(8)
	v_mfma_f32_16x16x32_bf16 v[104:107], v[68:71], v[116:119], v[104:107]
	v_mfma_f32_16x16x32_bf16 v[100:103], v[68:71], v[120:123], v[100:103]
	s_waitcnt lgkmcnt(7)
	s_add_u32 s98, s98, 0x2000
	s_addc_u32 s99, s99, 0
	global_load_dword v244, v151, s[98:99]
	v_mfma_f32_16x16x32_bf16 v[112:115], v[72:75], v[116:119], v[112:115]
	v_mfma_f32_16x16x32_bf16 v[108:111], v[72:75], v[120:123], v[108:111]
	s_waitcnt lgkmcnt(6)
	v_mfma_f32_16x16x32_bf16 v[84:87], v[76:79], v[116:119], v[84:87]
	v_cvt_pk_bf16_f32 v116, v36, v37
	v_cvt_pk_bf16_f32 v117, v38, v39
	v_cvt_pk_bf16_f32 v118, v44, v45
	v_mfma_f32_16x16x32_bf16 v[88:91], v[76:79], v[120:123], v[88:91]
	v_cvt_pk_bf16_f32 v119, v46, v47
	v_cvt_pk_bf16_f32 v120, v40, v41
	s_add_u32 s98, s98, 0x2000
	s_addc_u32 s99, s99, 0
	global_load_dword v243, v151, s[98:99]
	v_cvt_pk_bf16_f32 v121, v42, v43
	v_cvt_pk_bf16_f32 v122, v48, v49
	v_cvt_pk_bf16_f32 v123, v50, v51
	s_waitcnt lgkmcnt(5)
	v_mfma_f32_16x16x32_bf16 v[96:99], v[80:83], v[116:119], v[96:99]
	v_mfma_f32_16x16x32_bf16 v[92:95], v[80:83], v[120:123], v[92:95]
	s_waitcnt lgkmcnt(4)
	v_mfma_f32_16x16x32_bf16 v[104:107], v[128:131], v[116:119], v[104:107]
	v_mfma_f32_16x16x32_bf16 v[100:103], v[128:131], v[120:123], v[100:103]
	s_waitcnt lgkmcnt(3)
	s_add_u32 s98, s98, 0x2000
	s_addc_u32 s99, s99, 0
	global_load_dword v242, v151, s[98:99]
	v_mfma_f32_16x16x32_bf16 v[112:115], v[132:135], v[116:119], v[112:115]
	v_mfma_f32_16x16x32_bf16 v[108:111], v[132:135], v[120:123], v[108:111]
	s_waitcnt lgkmcnt(2)
	v_mfma_f32_16x16x32_bf16 v[84:87], v[136:139], v[116:119], v[84:87]
	v_mfma_f32_16x16x32_bf16 v[116:119], v[136:139], v[120:123], v[88:91]
	s_nop 2
	v_cvt_pk_bf16_f32 v88, v52, v53
	v_cvt_pk_bf16_f32 v89, v54, v55
	v_cvt_pk_bf16_f32 v90, v60, v61
	v_cvt_pk_bf16_f32 v91, v62, v63
	s_add_u32 s98, s98, 0x2000
	s_addc_u32 s99, s99, 0
	global_load_dword v241, v151, s[98:99]
	v_cvt_pk_bf16_f32 v120, v56, v57
	v_cvt_pk_bf16_f32 v121, v58, v59
	v_cvt_pk_bf16_f32 v122, v64, v65
	v_cvt_pk_bf16_f32 v123, v66, v67
	s_waitcnt lgkmcnt(1)
	v_mfma_f32_16x16x32_bf16 v[128:131], v[140:143], v[88:91], v[96:99]
	v_mfma_f32_16x16x32_bf16 v[124:127], v[140:143], v[120:123], v[92:95]
	s_nop 2
	ds_read2_b64 v[92:95], v226 offset0:24 offset1:28
	s_nop 2
	s_add_u32 s98, s98, 0x2000
	s_addc_u32 s99, s99, 0
	global_load_dword v240, v151, s[98:99]
	s_waitcnt lgkmcnt(1)
	v_mfma_f32_16x16x32_bf16 v[104:107], v[144:147], v[88:91], v[104:107]
	v_mfma_f32_16x16x32_bf16 v[132:135], v[144:147], v[120:123], v[100:103]
	s_waitcnt lgkmcnt(0)
	v_mfma_f32_16x16x32_bf16 v[100:103], v[92:95], v[88:91], v[112:115]
	v_mfma_f32_16x16x32_bf16 v[96:99], v[92:95], v[120:123], v[108:111]
	ds_read2_b64 v[92:95], v227 offset0:24 offset1:28
	s_waitcnt lgkmcnt(0)
	v_mfma_f32_16x16x32_bf16 v[88:91], v[92:95], v[88:91], v[84:87]
	v_mfma_f32_16x16x32_bf16 v[92:95], v[92:95], v[120:123], v[116:119]
	s_add_u32 s98, s98, 0x2000
	s_addc_u32 s99, s99, 0
	global_load_dword v239, v151, s[98:99]
	v_add_u32_e32 v120, s33, v156
	s_nop 0
	ds_read_b128 v[84:87], v120
	ds_read_b128 v[68:71], v120 offset:64
	ds_read_b128 v[72:75], v120 offset:128
	s_nop 0
	s_waitcnt lgkmcnt(2)
	v_mul_f32_e32 v2, 0x3fb8aa3b, v84
	v_mul_f32_e32 v84, 0x3fb8aa3b, v86
	v_exp_f32_e32 v108, v84
	s_add_u32 s98, s98, 0x2000
	s_addc_u32 s99, s99, 0
	global_load_dword v238, v151, s[98:99]
	v_mul_f32_e32 v84, 0x3fb8aa3b, v87
	v_exp_f32_e32 v109, v84
	v_mul_f32_e32 v3, 0x3fb8aa3b, v85
	v_exp_f32_e32 v2, v2
	v_exp_f32_e32 v3, v3
	v_pk_mul_f32 v[86:87], v[130:131], v[108:109]
	v_pk_mul_f32 v[118:119], v[126:127], v[108:109]
	v_pk_mul_f32 v[84:85], v[128:129], v[2:3]
	v_pk_mul_f32 v[116:117], v[124:125], v[2:3]
	s_waitcnt lgkmcnt(1)
	s_add_u32 s98, s98, 0x2000
	s_addc_u32 s99, s99, 0
	global_load_dword v237, v151, s[98:99]
	v_mul_f32_e32 v2, 0x3fb8aa3b, v68
	v_mul_f32_e32 v108, 0x3fb8aa3b, v70
	v_mul_f32_e32 v3, 0x3fb8aa3b, v69
	v_exp_f32_e32 v112, v108
	v_mul_f32_e32 v108, 0x3fb8aa3b, v71
	v_exp_f32_e32 v2, v2
	v_exp_f32_e32 v3, v3
	v_exp_f32_e32 v113, v108
	v_pk_mul_f32 v[108:109], v[104:105], v[2:3]
	v_pk_mul_f32 v[110:111], v[106:107], v[112:113]
	s_add_u32 s98, s98, 0x2000
	s_addc_u32 s99, s99, 0
	global_load_dword v236, v151, s[98:99]
	v_pk_mul_f32 v[114:115], v[134:135], v[112:113]
	v_pk_mul_f32 v[112:113], v[132:133], v[2:3]
	s_waitcnt lgkmcnt(0)
	v_mul_f32_e32 v2, 0x3fb8aa3b, v72
	v_mul_f32_e32 v3, 0x3fb8aa3b, v73
	v_mul_f32_e32 v104, 0x3fb8aa3b, v74
	v_mul_f32_e32 v105, 0x3fb8aa3b, v75
	v_exp_f32_e32 v2, v2
	v_exp_f32_e32 v3, v3
	v_exp_f32_e32 v104, v104
	v_exp_f32_e32 v105, v105
	v_pk_mul_f32 v[100:101], v[100:101], v[2:3]
	v_pk_mul_f32 v[102:103], v[102:103], v[104:105]
	v_pk_mul_f32 v[106:107], v[98:99], v[104:105]
	v_pk_mul_f32 v[104:105], v[96:97], v[2:3]
	ds_read_b128 v[96:99], v120 offset:192
	s_waitcnt lgkmcnt(0)
	s_barrier
	s_cmp_lg_u64 s[6:7], 0
	s_cbranch_scc0 .Lprio35_a
	s_setprio 1

.Lp1be_chk:
	s_cmpk_lt_u32 s83, 0x80
	s_cbranch_scc1 .LBB0_495
	s_waitcnt vmcnt(0) lgkmcnt(0)
	v_readlane_b32 s86, v254, 50
	v_readlane_b32 s87, v254, 51
	v_readlane_b32 s74, v255, 1
	v_readlane_b32 s78, v254, 62
	v_readlane_b32 s90, v254, 54
	v_readlane_b32 s92, v254, 52
	v_readlane_b32 s75, v255, 2
	v_readlane_b32 s79, v254, 63
	v_readlane_b32 s77, v254, 61
	v_readlane_b32 s82, v254, 58
	v_readlane_b32 s91, v254, 55
	v_readlane_b32 s93, v254, 53
	s_addk_i32 s83, 0x380
	s_movk_i32 s80, 0x80
	s_mov_b32 s98, 1
	s_movk_i32 s99, 0x600
	s_movk_i32 s100, 0x5ff
	s_branch .Lp1be_entry
.Lp1be_ret:
	v_readlane_b32 s80, v254, 59
	v_readlane_b32 s83, v255, 6
	s_mov_b32 s98, 0
	s_branch .LBB0_495

.LBB0_547:
	s_or_b64 exec, exec, s[0:1]
	s_mov_b32 s98, 0
	s_movk_i32 s99, 0x400
	s_movk_i32 s100, 0x3ff
.Lp1be_entry:
	s_add_u32 s4, s74, 0xac00000
	s_addc_u32 s5, s75, 0
	v_mov_b32_e32 v11, v179
	v_readlane_b32 s88, v254, 56
	s_waitcnt lgkmcnt(0)
	s_barrier
	s_cmp_gt_u32 s83, s100
	v_readfirstlane_b32 s2, v11
	v_readlane_b32 s85, v255, 3
	v_readlane_b32 s76, v255, 0
	v_readlane_b32 s89, v254, 57
	s_cbranch_scc1 .LBB0_567
	v_lshlrev_b32_e32 v0, 4, v11
	v_add_u32_e32 v1, 0x2000, v0
	v_ashrrev_i32_e32 v2, 31, v1
	v_lshrrev_b32_e32 v2, 22, v2
	v_add_u32_e32 v2, v1, v2
	v_ashrrev_i32_e32 v8, 10, v2
	v_mul_i32_i24_e32 v2, 0x400, v8
	v_sub_u32_e32 v1, v1, v2
	v_lshrrev_b32_e32 v2, 4, v1
	v_bitop3_b32 v1, v2, v1, 32 bitop3:0x6c
	v_ashrrev_i32_e32 v2, 31, v1
	v_lshrrev_b32_e32 v2, 26, v2
	v_add_u32_e32 v2, v1, v2
	v_lshlrev_b32_e32 v3, 3, v8
	v_ashrrev_i32_e32 v9, 6, v2
	v_and_b32_e32 v3, -16, v3
	v_add_u32_e32 v3, v9, v3
	v_and_b32_e32 v4, 3, v9
	s_mov_b32 s0, 0x1fffe0
	v_lshrrev_b32_e32 v5, 2, v3
	v_lshlrev_b32_e32 v6, 1, v3
	v_and_b32_e32 v2, 0xc0, v2
	v_and_or_b32 v4, v3, s0, v4
	v_and_b32_e32 v5, 4, v5
	v_and_b32_e32 v6, 24, v6
	v_sub_u32_e32 v1, v1, v2
	v_mov_b32_e32 v2, 1
	v_or3_b32 v4, v4, v5, v6
	v_lshlrev_b32_e32 v5, 5, v8
	v_ashrrev_i16_sdwa v1, v2, sext(v1) dst_sel:DWORD dst_unused:UNUSED_PAD src0_sel:DWORD src1_sel:BYTE_0
	v_and_b32_e32 v5, 32, v5
	v_bfe_i32 v10, v1, 0, 16
	v_add_lshl_u32 v1, v5, v10, 1
	v_lshl_add_u32 v144, v4, 11, v1
	v_lshl_add_u32 v146, v3, 11, v1
	v_bfe_i32 v1, v11, 27, 1
	v_lshrrev_b32_e32 v1, 22, v1
	v_add_u32_e32 v1, v0, v1
	v_and_b32_e32 v1, 0xfffffc00, v1
	v_sub_u32_e32 v0, v0, v1
	v_lshrrev_b32_e32 v1, 4, v0
	v_ashrrev_i32_e32 v3, 31, v11
	v_bitop3_b32 v0, v1, v0, 32 bitop3:0x6c
	v_lshrrev_b32_e32 v3, 26, v3
	v_ashrrev_i32_e32 v1, 31, v0
	v_add_u32_e32 v3, v11, v3
	v_lshrrev_b32_e32 v1, 26, v1
	v_ashrrev_i32_e32 v13, 6, v3
	v_add_u32_e32 v1, v0, v1
	v_lshlrev_b32_e32 v3, 3, v13
	v_ashrrev_i32_e32 v12, 6, v1
	v_and_b32_e32 v3, -16, v3
	s_add_u32 s26, s74, 0x1d00000
	v_add_u32_e32 v3, v12, v3
	v_and_b32_e32 v4, 3, v12
	s_addc_u32 s27, s75, 0
	v_and_or_b32 v4, v3, s0, v4
	s_and_b32 s0, s83, 7
	s_lshr_b32 s1, s83, 3
	s_mulk_i32 s0, 0xc0
	s_add_i32 s0, s0, s1
	s_mul_i32 s1, s0, 0xaaab
	s_lshr_b32 s1, s1, 22
	s_lshl_b32 s7, s1, 3
	s_mulk_i32 s1, 0x60
	s_sub_i32 s0, s0, s1
	v_lshrrev_b32_e32 v5, 2, v3
	v_lshlrev_b32_e32 v6, 1, v3
	v_and_b32_e32 v1, 0xc0, v1
	s_and_b32 s1, s0, 7
	s_ashr_i32 s6, s2, 6
	v_and_b32_e32 v5, 4, v5
	v_and_b32_e32 v6, 24, v6
	v_sub_u32_e32 v0, v0, v1
	s_or_b32 s7, s1, s7
	s_lshr_b32 s1, s7, 3
	s_lshr_b32 s3, s7, 4
	s_xor_b32 s1, s1, s3
	s_and_b32 s1, s1, 1
	s_xor_b32 s1, s1, 1
	s_mul_i32 s1, s1, 24
	s_xor_b32 s7, s7, s1
	s_bfe_u32 s8, s0, 0x50003
	s_ashr_i32 s3, s2, 8
	s_lshl_b32 s28, s6, 10
	v_or3_b32 v4, v4, v5, v6
	v_lshlrev_b32_e32 v5, 5, v13
	v_ashrrev_i16_sdwa v0, v2, sext(v0) dst_sel:DWORD dst_unused:UNUSED_PAD src0_sel:DWORD src1_sel:BYTE_0
	s_lshl_b32 s9, s7, 19
	s_lshl_b32 s0, s8, 19
	v_and_b32_e32 v5, 32, v5
	v_bfe_i32 v14, v0, 0, 16
	s_add_u32 s22, s26, s0
	v_add_lshl_u32 v0, v5, v14, 1
	s_addc_u32 s23, s27, 0
	s_add_i32 s29, s28, 0
	v_lshl_add_u32 v148, v4, 11, v0
	s_add_i32 m0, s29, 0x10000
	v_lshl_add_u32 v150, v3, 11, v0
	global_load_lds_dwordx4 v148, s[22:23]
	s_add_i32 m0, s29, 0x12000
	s_add_u32 s0, s22, 0x40000
	global_load_lds_dwordx4 v144, s[22:23]
	s_addc_u32 s1, s23, 0
	s_add_i32 m0, s29, 0x14000
	v_mov_b32_e32 v153, 0
	global_load_lds_dwordx4 v148, s[0:1]
	s_add_i32 m0, s29, 0x16000
	s_add_u32 s20, s90, s9
	s_addc_u32 s21, s91, 0
	s_add_i32 s30, s29, 0x2000
	global_load_lds_dwordx4 v144, s[0:1]
	s_mov_b32 m0, s29
	s_add_u32 s0, s20, 0x40000
	global_load_lds_dwordx4 v150, s[20:21]
	s_mov_b32 m0, s30
	s_addc_u32 s1, s21, 0
	s_add_i32 s31, s29, 0x4000
	global_load_lds_dwordx4 v146, s[20:21]
	s_mov_b32 m0, s31
	s_add_i32 s34, s29, 0x6000
	global_load_lds_dwordx4 v150, s[0:1]
	s_mov_b32 m0, s34
	v_mov_b32_e32 v149, v153
	global_load_lds_dwordx4 v146, s[0:1]
	v_mov_b32_e32 v145, v153
	v_mov_b32_e32 v151, v153
	v_mov_b32_e32 v147, v153
	s_cmp_eq_u32 s3, 1
	s_mov_b32 s35, 0
	v_lshl_add_u64 v[6:7], s[22:23], 0, v[148:149]
	v_lshl_add_u64 v[2:3], s[22:23], 0, v[144:145]
	v_lshl_add_u64 v[0:1], s[20:21], 0, v[150:151]
	s_cselect_b64 s[0:1], -1, 0
	s_cmp_lg_u32 s3, 1
	v_lshl_add_u64 v[4:5], s[20:21], 0, v[146:147]
	s_cbranch_scc1 .LBB0_550
	s_barrier
.LBB0_550:
	s_lshl_b32 s6, s6, 5
	s_and_b32 s33, 0xffff, s7
	s_and_b32 s11, s6, 0x60
	s_mov_b64 s[6:7], 0x80
	s_add_i32 m0, s29, 0x18000
	v_lshl_add_u64 v[6:7], v[6:7], 0, s[6:7]
	s_and_b32 s45, 0xffff, s8
	s_lshl_b32 s10, s3, 13
	s_lshl_b32 s12, s11, 7
	s_waitcnt vmcnt(2)
	s_barrier
	global_load_lds_dwordx4 v[6:7], off
	v_lshl_add_u64 v[2:3], v[2:3], 0, s[6:7]
	s_add_i32 m0, s29, 0x1a000
	s_add_i32 s36, s29, 0x8000
	s_add_i32 s37, s29, 0xa000
	global_load_lds_dwordx4 v[2:3], off
	v_lshl_add_u64 v[0:1], v[0:1], 0, s[6:7]
	s_mov_b32 m0, s36
	s_add_u32 s8, s22, 0x40080
	global_load_lds_dwordx4 v[0:1], off
	v_lshl_add_u64 v[0:1], v[4:5], 0, s[6:7]
	s_mov_b32 m0, s37
	s_addc_u32 s9, s23, 0
	global_load_lds_dwordx4 v[0:1], off
	s_add_i32 m0, s29, 0x1c000
	v_lshl_add_u64 v[0:1], s[8:9], 0, v[148:149]
	global_load_lds_dwordx4 v[0:1], off
	v_lshl_add_u64 v[0:1], s[8:9], 0, v[144:145]
	s_add_i32 m0, s29, 0x1e000
	v_readlane_b32 s48, v254, 0
	global_load_lds_dwordx4 v[0:1], off
	v_lshrrev_b32_e32 v1, 1, v11
	v_and_b32_e32 v1, 24, v1
	v_and_b32_e32 v0, 15, v11
	v_lshlrev_b32_e32 v2, 1, v1
	v_lshl_or_b32 v178, s3, 6, v0
	v_lshl_or_b32 v0, v0, 6, v2
	v_lshlrev_b32_e32 v2, 2, v11
	v_and_b32_e32 v2, 32, v2
	v_bitop3_b32 v3, v0, s10, v2 bitop3:0xde
	v_bitop3_b32 v180, v0, s12, v2 bitop3:0xde
	v_or_b32_e32 v0, s11, v1
	v_or_b32_e32 v181, 0xfffff800, v0
	v_lshlrev_b32_e32 v152, 1, v0
	v_lshlrev_b32_e32 v0, 14, v13
	v_and_b32_e32 v0, 0xffff8000, v0
	v_lshl_add_u32 v0, v12, 11, v0
	v_and_b32_e32 v1, 1, v13
	v_readlane_b32 s49, v254, 1
	v_readlane_b32 s50, v254, 2
	v_readlane_b32 s51, v254, 3
	v_readlane_b32 s60, v254, 12
	v_readlane_b32 s61, v254, 13
	v_lshl_or_b32 v0, v1, 6, v0
	s_cmpk_lt_u32 s2, 0x100
	v_readlane_b32 s62, v254, 14
	v_readlane_b32 s63, v254, 15
	s_mov_b64 s[48:49], s[60:61]
	v_lshl_add_u32 v156, v14, 1, v0
	v_lshlrev_b32_e32 v0, 14, v8
	s_cselect_b64 s[8:9], -1, 0
	s_ashr_i32 s38, s80, 31
	s_mov_b64 s[50:51], s[62:63]
	v_and_b32_e32 v0, 0xffff8000, v0
	s_waitcnt vmcnt(6)
	s_add_u32 s10, s50, 0x1000
	v_lshl_add_u32 v0, v9, 11, v0
	v_and_b32_e32 v1, 1, v8
	s_addc_u32 s11, s51, 0
	v_lshl_or_b32 v0, v1, 6, v0
	s_add_i32 s40, 0, 0x10000
	s_add_i32 s41, 0, 0x14000
	s_mov_b32 s39, s80
	v_lshl_add_u64 v[154:155], s[92:93], 0, v[152:153]
	v_mov_b32_e32 v157, v153
	v_lshl_add_u32 v158, v10, 1, v0
	v_mov_b32_e32 v159, v153
	v_mov_b32_e32 v160, s99
	v_mov_b32_e32 v161, 0
	v_mov_b32_e32 v162, s100
	v_mov_b32_e32 v163, 0
	v_add_u32_e32 v182, s40, v180
	v_add_u32_e32 v183, s41, v180
	v_add_u32_e32 v184, 0, v3
	s_mov_b32 s42, 0x40000
	s_mov_b32 s43, 0x48000
	s_mov_b32 s44, 0x50000
	s_barrier
	v_readlane_b32 s52, v254, 4
	v_readlane_b32 s53, v254, 5
	v_readlane_b32 s54, v254, 6
	v_readlane_b32 s55, v254, 7
	v_readlane_b32 s56, v254, 8
	v_readlane_b32 s57, v254, 9
	v_readlane_b32 s58, v254, 10
	v_readlane_b32 s59, v254, 11
	s_branch .LBB0_553

.LBB0_553:
	s_add_i32 s35, s35, 1
	s_mul_i32 s2, s35, s38
	s_mul_hi_u32 s3, s35, s39
	s_add_i32 s3, s3, s2
	s_mul_i32 s2, s35, s39
	s_add_u32 s16, s2, s83
	s_addc_u32 s17, s3, 0
	v_cmp_gt_i64_e32 vcc, s[16:17], v[162:163]
	v_cmp_lt_i64_e64 s[2:3], s[16:17], v[160:161]
	s_cbranch_vccnz .LBB0_555
	s_ashr_i32 s12, s16, 31
	s_lshr_b32 s12, s12, 29
	s_add_i32 s12, s16, s12
	s_ashr_i32 s13, s12, 3
	s_and_b32 s12, s12, -8
	s_sub_i32 s12, s16, s12
	s_cmp_lt_i32 s12, 0
	s_movk_i32 s14, 0xc1
	s_cselect_b32 s14, s14, 0xc0
	s_mul_i32 s12, s12, s14
	s_add_i32 s12, s12, s13
	s_mul_hi_i32 s13, s12, 0x2aaaaaab
	s_lshr_b32 s14, s13, 31
	s_ashr_i32 s13, s13, 4
	s_add_i32 s13, s13, s14
	s_lshl_b32 s14, s13, 3
	s_sub_i32 s15, 0x80, s14
	s_min_i32 s15, s15, 8
	s_abs_i32 s16, s15
	v_cvt_f32_u32_e32 v0, s16
	s_sub_i32 s18, 0, s16
	s_mulk_i32 s13, 0x60
	s_sub_i32 s13, s12, s13
	v_rcp_iflag_f32_e32 v0, v0
	s_abs_i32 s12, s13
	s_xor_b32 s17, s13, s15
	s_ashr_i32 s17, s17, 31
	v_mul_f32_e32 v0, 0x4f7ffffe, v0
	v_cvt_u32_f32_e32 v0, v0
	s_nop 0
	v_readfirstlane_b32 s19, v0
	s_mul_i32 s18, s18, s19
	s_mul_hi_u32 s18, s19, s18
	s_add_i32 s19, s19, s18
	s_mul_hi_u32 s18, s12, s19
	s_mul_i32 s19, s18, s16
	s_sub_i32 s12, s12, s19
	s_add_i32 s24, s18, 1
	s_sub_i32 s19, s12, s16
	s_cmp_ge_u32 s12, s16
	s_cselect_b32 s18, s24, s18
	s_cselect_b32 s12, s19, s12
	s_add_i32 s19, s18, 1
	s_cmp_ge_u32 s12, s16
	s_cselect_b32 s12, s19, s18
	s_xor_b32 s12, s12, s17
	s_sub_i32 s12, s12, s17
	s_mul_i32 s15, s12, s15
	s_sub_i32 s13, s13, s15
	s_add_i32 s14, s14, s13
	s_lshr_b32 s13, s14, 3
	s_lshr_b32 s15, s14, 4
	s_xor_b32 s13, s13, s15
	s_and_b32 s13, s13, 1
	s_xor_b32 s13, s13, 1
	s_mul_i32 s13, s13, 24
	s_xor_b32 s14, s14, s13

.LBB0_559:
	s_cmp_eq_u32 s98, 0
	s_cbranch_scc1 .Lp1be_nowait
	s_add_i32 s46, s33, 0x84
	s_cmp_gt_i32 s45, 7
	s_cselect_b32 s46, s46, s33
	s_lshr_b32 s47, s46, 5
	s_and_b32 s46, s46, 31
	s_add_i32 s46, s46, 2
	s_lshl_b32 s46, s46, 3
	s_lshl_b32 s47, s47, 5
	s_add_u32 s100, s74, 0x80000
	s_addc_u32 s101, s75, 0
	s_add_u32 s100, s100, s47
	s_addc_u32 s101, s101, 0
	v_mov_b32_e32 v165, 0
	s_movk_i32 s48, 0x200
.Lp1be_spin:
	global_load_dword v164, v165, s[100:101] sc1
	s_waitcnt vmcnt(0)
	v_readfirstlane_b32 s49, v164
	s_cmp_ge_u32 s49, s46
	s_cbranch_scc1 .Lp1be_nowait
	s_sleep 8
	s_add_i32 s48, s48, -1
	s_cmp_lg_u32 s48, 0
	s_cbranch_scc1 .Lp1be_spin

.LBB0_567:
	s_cmp_lg_u32 s98, 0
	s_cbranch_scc1 .Lp1be_ret
	s_waitcnt vmcnt(0)
	s_waitcnt vmcnt(0)
	s_barrier
	s_and_saveexec_b64 s[0:1], s[86:87]
	s_cbranch_execz .LBB0_619
	s_add_i32 s2, 0, 0x23fc0
	v_mov_b32_e32 v0, s2
	s_waitcnt vmcnt(0) expcnt(0) lgkmcnt(0)
	ds_read_b32 v2, v0
	s_add_i32 s2, 0, 0x23fc4
	v_mov_b32_e32 v0, s2
	ds_read_b32 v0, v0
	s_waitcnt lgkmcnt(1)
	v_cmp_ne_u32_e32 vcc, 0, v2
	s_cbranch_vccnz .LBB0_583
	s_add_u32 s2, s74, 0x80200
	s_addc_u32 s3, s75, 0
	s_add_u32 s6, s74, 0x80400
	s_addc_u32 s7, s75, 0
	s_add_u32 s8, s74, 0x80500
	s_addc_u32 s9, s75, 0
	s_add_u32 s10, s74, 0x80600
	s_addc_u32 s11, s75, 0
	s_add_u32 s12, s74, 0x80700
	s_addc_u32 s13, s75, 0
	s_add_u32 s14, s74, 0x80800
	s_addc_u32 s15, s75, 0
	s_add_u32 s16, s74, 0x80900
	s_addc_u32 s17, s75, 0
	s_add_u32 s18, s74, 0x80a00
	s_addc_u32 s19, s75, 0
	s_add_u32 s20, s74, 0x80b00
	s_addc_u32 s21, s75, 0
	s_add_u32 s22, s74, 0x80c00
	s_addc_u32 s23, s75, 0
	s_add_u32 s24, s74, 0x80d00
	s_addc_u32 s25, s75, 0
	s_add_u32 s26, s74, 0x80e00
	s_addc_u32 s27, s75, 0
	s_add_u32 s28, s74, 0x80f00
	s_addc_u32 s29, s75, 0
	s_add_u32 s30, s74, 0x81000
	s_addc_u32 s31, s75, 0
	s_add_u32 s34, s74, 0x81100
	s_addc_u32 s35, s75, 0
	s_add_u32 s36, s74, 0x81200
	s_addc_u32 s37, s75, 0
	s_mul_i32 s33, s81, s82
	s_add_u32 s38, s74, 0x81300
	s_mul_i32 s33, s33, s80
	s_addc_u32 s39, s75, 0
	s_mov_b32 s46, 1
	v_mov_b32_e32 v16, 0
	s_branch .LBB0_571
